# first QK MFMA of the first unrolled step issued right after the step barrier (as in the second step) in both dense-attention main loops
# baseline (speedup 1.0000x reference)
.LBB0_442:
	s_mov_b32 s30, s62
	v_mov_b64_e32 v[218:219], v[96:97]
	s_mov_b32 s63, s33
	s_mov_b32 s3, s61
	v_lshl_add_u32 v206, s36, 14, v241
	ds_read_b64_tr_b16 v[196:197], v206 offset:24576
	ds_read_b64_tr_b16 v[198:199], v206 offset:25088
	v_mfma_f32_32x32x16_bf16 v[112:127], v[188:191], v[156:159], 0
	v_add_f32_e32 v96, v80, v81
	v_add_f32_e32 v96, v82, v96
	v_add_f32_e32 v96, v83, v96
	v_add_f32_e32 v96, v84, v96
	v_add_f32_e32 v96, v85, v96
	v_cvt_pk_bf16_f32 v140, v80, v81
	v_cvt_pk_bf16_f32 v141, v82, v83
	ds_read_b64_tr_b16 v[80:81], v206 offset:28672
	ds_read_b64_tr_b16 v[82:83], v206 offset:29184
	v_add_f32_e32 v96, v86, v96
	v_add_f32_e32 v96, v87, v96
	v_add_f32_e32 v96, v88, v96
	v_add_f32_e32 v128, v89, v96
	v_mfma_f32_32x32x16_bf16 v[96:111], v[180:183], v[156:159], 0
	v_cvt_pk_bf16_f32 v142, v84, v85
	v_cvt_pk_bf16_f32 v143, v86, v87
	ds_read_b64_tr_b16 v[84:85], v206 offset:25600
	ds_read_b64_tr_b16 v[86:87], v206 offset:26112
	v_add_f32_e32 v128, v90, v128
	v_add_f32_e32 v128, v91, v128
	v_add_f32_e32 v128, v92, v128
	v_add_f32_e32 v128, v93, v128
	v_cvt_pk_bf16_f32 v136, v88, v89
	v_cvt_pk_bf16_f32 v137, v90, v91
	v_mfma_f32_32x32x16_bf16 v[112:127], v[184:187], v[152:155], v[112:127]
	ds_read_b64_tr_b16 v[88:89], v206 offset:29696
	ds_read_b64_tr_b16 v[90:91], v206 offset:30208
	v_mfma_f32_32x32x16_bf16 v[96:111], v[176:179], v[152:155], v[96:111]
	v_add_f32_e32 v128, v94, v128
	v_add_f32_e32 v128, v95, v128
	v_add_f32_e32 v128, v64, v128
	v_add_f32_e32 v128, v65, v128
	v_cvt_pk_bf16_f32 v138, v92, v93
	v_cvt_pk_bf16_f32 v139, v94, v95
	ds_read_b64_tr_b16 v[92:93], v206 offset:26624
	ds_read_b64_tr_b16 v[94:95], v206 offset:27136
	v_add_f32_e32 v128, v66, v128
	v_add_f32_e32 v128, v67, v128
	v_add_f32_e32 v128, v68, v128
	v_add_f32_e32 v128, v69, v128
	v_cvt_pk_bf16_f32 v132, v64, v65
	v_cvt_pk_bf16_f32 v133, v66, v67
	v_mfma_f32_32x32x16_bf16 v[112:127], v[172:175], v[148:151], v[112:127]
	ds_read_b64_tr_b16 v[200:201], v206 offset:30720
	ds_read_b64_tr_b16 v[202:203], v206 offset:31232
	v_mfma_f32_32x32x16_bf16 v[96:111], v[168:171], v[148:151], v[96:111]
	v_add_f32_e32 v64, v70, v128
	v_add_f32_e32 v64, v71, v64
	v_add_f32_e32 v64, v72, v64
	v_add_f32_e32 v64, v73, v64
	v_cvt_pk_bf16_f32 v134, v68, v69
	v_cvt_pk_bf16_f32 v135, v70, v71
	ds_read_b64_tr_b16 v[242:243], v206 offset:27648
	ds_read_b64_tr_b16 v[244:245], v206 offset:28160
	v_add_f32_e32 v64, v74, v64
	v_add_f32_e32 v64, v75, v64
	v_add_f32_e32 v64, v76, v64
	v_add_f32_e32 v64, v77, v64
	v_cvt_pk_bf16_f32 v128, v72, v73
	v_cvt_pk_bf16_f32 v129, v74, v75
	v_mfma_f32_32x32x16_bf16 v[112:127], v[164:167], v[144:147], v[112:127]
	ds_read_b64_tr_b16 v[72:73], v206 offset:31744
	ds_read_b64_tr_b16 v[74:75], v206 offset:32256
	v_mfma_f32_32x32x16_bf16 v[96:111], v[160:163], v[144:147], v[96:111]
	v_add_f32_e32 v64, v78, v64
	v_add_f32_e32 v64, v79, v64
	v_add_f32_e32 v64, 0, v64
	v_cvt_pk_bf16_f32 v130, v76, v77
	v_cvt_pk_bf16_f32 v131, v78, v79
	v_add_f32_e32 v188, v204, v64
	s_waitcnt lgkmcnt(14)
	v_mfma_f32_32x32x16_bf16 v[48:63], v[140:143], v[196:199], v[48:63]
	v_exp_f32_e32 v112, v112
	v_exp_f32_e32 v113, v113
	ds_read_b64_tr_b16 v[76:77], v206 offset:32768
	ds_read_b64_tr_b16 v[78:79], v206 offset:33280
	s_waitcnt lgkmcnt(14)
	v_mfma_f32_32x32x16_bf16 v[32:47], v[140:143], v[80:83], v[32:47]
	v_exp_f32_e32 v114, v114
	v_exp_f32_e32 v115, v115
	ds_read_b64_tr_b16 v[80:81], v206 offset:36864
	ds_read_b64_tr_b16 v[82:83], v206 offset:37376
	s_waitcnt lgkmcnt(14)
	v_mfma_f32_32x32x16_bf16 v[48:63], v[136:139], v[84:87], v[48:63]
	v_exp_f32_e32 v116, v116
	v_exp_f32_e32 v117, v117
	ds_read_b64_tr_b16 v[84:85], v206 offset:33792
	ds_read_b64_tr_b16 v[86:87], v206 offset:34304
	s_waitcnt lgkmcnt(14)
	v_mfma_f32_32x32x16_bf16 v[32:47], v[136:139], v[88:91], v[32:47]
	v_exp_f32_e32 v118, v118
	v_exp_f32_e32 v119, v119
	ds_read_b64_tr_b16 v[88:89], v206 offset:37888
	ds_read_b64_tr_b16 v[90:91], v206 offset:38400
	s_waitcnt lgkmcnt(14)
	v_mfma_f32_32x32x16_bf16 v[48:63], v[132:135], v[92:95], v[48:63]
	v_exp_f32_e32 v120, v120
	v_exp_f32_e32 v121, v121
	ds_read_b64_tr_b16 v[92:93], v206 offset:34816
	ds_read_b64_tr_b16 v[94:95], v206 offset:35328
	s_waitcnt lgkmcnt(14)
	v_mfma_f32_32x32x16_bf16 v[32:47], v[132:135], v[200:203], v[32:47]
	v_exp_f32_e32 v122, v122
	v_exp_f32_e32 v123, v123
	ds_read_b64_tr_b16 v[196:197], v206 offset:38912
	ds_read_b64_tr_b16 v[198:199], v206 offset:39424
	s_waitcnt lgkmcnt(14)
	v_mfma_f32_32x32x16_bf16 v[48:63], v[128:131], v[242:245], v[48:63]
	v_exp_f32_e32 v124, v124
	v_exp_f32_e32 v125, v125
	ds_read_b64_tr_b16 v[200:201], v206 offset:35840
	ds_read_b64_tr_b16 v[202:203], v206 offset:36352
	s_waitcnt lgkmcnt(14)
	v_mfma_f32_32x32x16_bf16 v[32:47], v[128:131], v[72:75], v[32:47]
	v_exp_f32_e32 v126, v126
	v_exp_f32_e32 v127, v127
	ds_read_b64_tr_b16 v[72:73], v206 offset:39936
	ds_read_b64_tr_b16 v[74:75], v206 offset:40448
	s_waitcnt lgkmcnt(14)
	v_mfma_f32_32x32x16_bf16 v[16:31], v[140:143], v[76:79], v[16:31]
	v_exp_f32_e32 v96, v96
	v_exp_f32_e32 v97, v97
	s_lshl_b32 s31, s62, 13
	v_add_u32_e32 v160, s31, v239
	ds_read_b128 v[68:71], v160
	ds_read_b128 v[64:67], v160 offset:512
	s_waitcnt lgkmcnt(14)
	v_mfma_f32_32x32x16_bf16 v[0:15], v[140:143], v[80:83], v[0:15]
	v_exp_f32_e32 v98, v98
	v_exp_f32_e32 v99, v99
	ds_read_b128 v[180:183], v160 offset:2048
	ds_read_b128 v[176:179], v160 offset:2560
	s_waitcnt lgkmcnt(14)
	v_mfma_f32_32x32x16_bf16 v[16:31], v[136:139], v[84:87], v[16:31]
	v_exp_f32_e32 v100, v100
	v_exp_f32_e32 v101, v101
	ds_read_b128 v[172:175], v160 offset:4096
	ds_read_b128 v[168:171], v160 offset:4608
	s_waitcnt lgkmcnt(14)
	v_mfma_f32_32x32x16_bf16 v[0:15], v[136:139], v[88:91], v[0:15]
	v_exp_f32_e32 v102, v102
	v_exp_f32_e32 v103, v103
	ds_read_b128 v[164:167], v160 offset:6144
	ds_read_b128 v[160:163], v160 offset:6656
	s_waitcnt lgkmcnt(14)
	v_mfma_f32_32x32x16_bf16 v[16:31], v[132:135], v[92:95], v[16:31]
	v_exp_f32_e32 v104, v104
	v_exp_f32_e32 v105, v105
	v_lshl_add_u64 v[246:247], v[194:195], 0, s[4:5]
	s_mov_b64 s[34:35], 0xb622a00
	s_lshl_b32 s31, s61, 13
	v_lshl_add_u64 v[250:251], v[246:247], 0, s[34:35]
	s_add_i32 s31, s31, s58
	s_mov_b32 m0, s31
	s_nop 0
	global_load_lds_dwordx4 v[250:251], off
	s_waitcnt lgkmcnt(12)
	v_mfma_f32_32x32x16_bf16 v[0:15], v[132:135], v[196:199], v[0:15]
	v_exp_f32_e32 v106, v106
	v_exp_f32_e32 v107, v107
	v_lshl_add_u64 v[248:249], v[192:193], 0, s[4:5]
	s_mov_b64 s[34:35], 0xb412e00
	s_lshl_b32 s64, s62, 14
	v_lshl_add_u64 v[250:251], v[248:249], 0, s[34:35]
	s_add_i32 s31, s64, s59
	s_mov_b32 m0, s31
	s_nop 0
	global_load_lds_dwordx4 v[250:251], off
	s_waitcnt lgkmcnt(10)
	v_mfma_f32_32x32x16_bf16 v[16:31], v[128:131], v[200:203], v[16:31]
	v_exp_f32_e32 v108, v108
	v_exp_f32_e32 v109, v109
	s_mov_b64 s[34:35], 0xb412e80
	v_lshl_add_u64 v[250:251], v[248:249], 0, s[34:35]
	s_addk_i32 s31, 0x2000
	s_mov_b32 m0, s31
	s_nop 0
	global_load_lds_dwordx4 v[250:251], off
	s_waitcnt lgkmcnt(8)
	v_mfma_f32_32x32x16_bf16 v[0:15], v[128:131], v[72:75], v[0:15]
	v_exp_f32_e32 v110, v110
	v_exp_f32_e32 v111, v111
	s_waitcnt vmcnt(3) lgkmcnt(0)
	s_barrier
	s_add_i32 s33, s62, 1
	s_cmp_lg_u32 s62, 2
	s_cselect_b32 s61, s33, 0
	v_lshl_add_u32 v200, s3, 14, v241
	ds_read_b64_tr_b16 v[196:197], v200 offset:24576
	ds_read_b64_tr_b16 v[198:199], v200 offset:25088
	v_mfma_f32_32x32x16_bf16 v[80:95], v[68:71], v[156:159], 0
	v_add_f32_e32 v72, v112, v113
	v_add_f32_e32 v72, v114, v72
	v_add_f32_e32 v72, v115, v72
	v_add_f32_e32 v72, v116, v72
	v_add_f32_e32 v72, v117, v72
	v_cvt_pk_bf16_f32 v140, v112, v113
	v_cvt_pk_bf16_f32 v141, v114, v115
	ds_read_b64_tr_b16 v[112:113], v200 offset:28672
	ds_read_b64_tr_b16 v[114:115], v200 offset:29184
	v_add_f32_e32 v68, v118, v72
	v_add_f32_e32 v68, v119, v68
	v_add_f32_e32 v68, v120, v68
	v_add_f32_e32 v128, v121, v68
	v_mfma_f32_32x32x16_bf16 v[64:79], v[64:67], v[156:159], 0
	v_cvt_pk_bf16_f32 v142, v116, v117
	v_cvt_pk_bf16_f32 v143, v118, v119
	ds_read_b64_tr_b16 v[116:117], v200 offset:25600
	ds_read_b64_tr_b16 v[118:119], v200 offset:26112
	v_mfma_f32_32x32x16_bf16 v[80:95], v[180:183], v[152:155], v[80:95]
	v_add_f32_e32 v128, v122, v128
	v_add_f32_e32 v128, v123, v128
	v_add_f32_e32 v128, v124, v128
	v_add_f32_e32 v128, v125, v128
	v_cvt_pk_bf16_f32 v136, v120, v121
	v_cvt_pk_bf16_f32 v137, v122, v123
	ds_read_b64_tr_b16 v[120:121], v200 offset:29696
	ds_read_b64_tr_b16 v[122:123], v200 offset:30208
	v_mfma_f32_32x32x16_bf16 v[64:79], v[176:179], v[152:155], v[64:79]
	v_add_f32_e32 v128, v126, v128
	v_add_f32_e32 v128, v127, v128
	v_add_f32_e32 v128, v96, v128
	v_add_f32_e32 v128, v97, v128
	v_cvt_pk_bf16_f32 v138, v124, v125
	v_cvt_pk_bf16_f32 v139, v126, v127
	ds_read_b64_tr_b16 v[124:125], v200 offset:26624
	ds_read_b64_tr_b16 v[126:127], v200 offset:27136
	v_mfma_f32_32x32x16_bf16 v[80:95], v[172:175], v[148:151], v[80:95]
	v_add_f32_e32 v128, v98, v128
	v_add_f32_e32 v128, v99, v128
	v_add_f32_e32 v128, v100, v128
	v_add_f32_e32 v128, v101, v128
	v_cvt_pk_bf16_f32 v132, v96, v97
	v_cvt_pk_bf16_f32 v133, v98, v99
	ds_read_b64_tr_b16 v[96:97], v200 offset:30720
	ds_read_b64_tr_b16 v[98:99], v200 offset:31232
	v_mfma_f32_32x32x16_bf16 v[64:79], v[168:171], v[148:151], v[64:79]
	v_add_f32_e32 v128, v102, v128
	v_add_f32_e32 v128, v103, v128
	v_add_f32_e32 v128, v104, v128
	v_add_f32_e32 v128, v105, v128
	v_cvt_pk_bf16_f32 v134, v100, v101
	v_cvt_pk_bf16_f32 v135, v102, v103
	ds_read_b64_tr_b16 v[100:101], v200 offset:27648
	ds_read_b64_tr_b16 v[102:103], v200 offset:28160
	v_mfma_f32_32x32x16_bf16 v[80:95], v[164:167], v[144:147], v[80:95]
	v_add_f32_e32 v128, v106, v128
	v_add_f32_e32 v128, v107, v128
	v_add_f32_e32 v128, v108, v128
	v_add_f32_e32 v164, v109, v128
	v_cvt_pk_bf16_f32 v128, v104, v105
	v_cvt_pk_bf16_f32 v129, v106, v107
	ds_read_b64_tr_b16 v[104:105], v200 offset:31744
	ds_read_b64_tr_b16 v[106:107], v200 offset:32256
	v_mfma_f32_32x32x16_bf16 v[64:79], v[160:163], v[144:147], v[64:79]
	v_add_f32_e32 v130, v110, v164
	v_add_f32_e32 v130, v111, v130
	v_add_f32_e32 v160, 0, v130
	v_cvt_pk_bf16_f32 v130, v108, v109
	v_cvt_pk_bf16_f32 v131, v110, v111
	v_add_f32_e32 v204, v188, v160
	s_add_i32 s60, s60, 2
	s_waitcnt lgkmcnt(14)
	v_mfma_f32_32x32x16_bf16 v[48:63], v[140:143], v[196:199], v[48:63]
	v_exp_f32_e32 v80, v80
	v_exp_f32_e32 v81, v81
	ds_read_b64_tr_b16 v[108:109], v200 offset:32768
	ds_read_b64_tr_b16 v[110:111], v200 offset:33280
	s_waitcnt lgkmcnt(14)
	v_mfma_f32_32x32x16_bf16 v[32:47], v[140:143], v[112:115], v[32:47]
	v_exp_f32_e32 v82, v82
	v_exp_f32_e32 v83, v83
	ds_read_b64_tr_b16 v[112:113], v200 offset:36864
	ds_read_b64_tr_b16 v[114:115], v200 offset:37376
	s_waitcnt lgkmcnt(14)
	v_mfma_f32_32x32x16_bf16 v[48:63], v[136:139], v[116:119], v[48:63]
	v_exp_f32_e32 v84, v84
	v_exp_f32_e32 v85, v85
	ds_read_b64_tr_b16 v[116:117], v200 offset:33792
	ds_read_b64_tr_b16 v[118:119], v200 offset:34304
	s_waitcnt lgkmcnt(14)
	v_mfma_f32_32x32x16_bf16 v[32:47], v[136:139], v[120:123], v[32:47]
	v_exp_f32_e32 v86, v86
	v_exp_f32_e32 v87, v87
	ds_read_b64_tr_b16 v[120:121], v200 offset:37888
	ds_read_b64_tr_b16 v[122:123], v200 offset:38400
	s_waitcnt lgkmcnt(14)
	v_mfma_f32_32x32x16_bf16 v[48:63], v[132:135], v[124:127], v[48:63]
	v_exp_f32_e32 v88, v88
	v_exp_f32_e32 v89, v89
	ds_read_b64_tr_b16 v[124:125], v200 offset:34816
	ds_read_b64_tr_b16 v[126:127], v200 offset:35328
	s_waitcnt lgkmcnt(14)
	v_mfma_f32_32x32x16_bf16 v[32:47], v[132:135], v[96:99], v[32:47]
	v_exp_f32_e32 v90, v90
	v_exp_f32_e32 v91, v91
	ds_read_b64_tr_b16 v[96:97], v200 offset:38912
	ds_read_b64_tr_b16 v[98:99], v200 offset:39424
	s_waitcnt lgkmcnt(14)
	v_mfma_f32_32x32x16_bf16 v[48:63], v[128:131], v[100:103], v[48:63]
	v_exp_f32_e32 v92, v92
	v_exp_f32_e32 v93, v93
	ds_read_b64_tr_b16 v[100:101], v200 offset:35840
	ds_read_b64_tr_b16 v[102:103], v200 offset:36352
	s_waitcnt lgkmcnt(14)
	v_mfma_f32_32x32x16_bf16 v[32:47], v[128:131], v[104:107], v[32:47]
	v_exp_f32_e32 v94, v94
	v_exp_f32_e32 v95, v95
	ds_read_b64_tr_b16 v[104:105], v200 offset:39936
	ds_read_b64_tr_b16 v[106:107], v200 offset:40448
	s_waitcnt lgkmcnt(14)
	v_mfma_f32_32x32x16_bf16 v[16:31], v[140:143], v[108:111], v[16:31]
	v_exp_f32_e32 v64, v64
	v_exp_f32_e32 v65, v65
	v_lshl_add_u32 v160, s61, 13, v239
	ds_read_b128 v[188:191], v160
	ds_read_b128 v[180:183], v160 offset:512
	s_waitcnt lgkmcnt(14)
	v_mfma_f32_32x32x16_bf16 v[0:15], v[140:143], v[112:115], v[0:15]
	v_exp_f32_e32 v66, v66
	v_exp_f32_e32 v67, v67
	ds_read_b128 v[184:187], v160 offset:2048
	ds_read_b128 v[176:179], v160 offset:2560
	s_waitcnt lgkmcnt(14)
	v_mfma_f32_32x32x16_bf16 v[16:31], v[136:139], v[116:119], v[16:31]
	v_exp_f32_e32 v68, v68
	v_exp_f32_e32 v69, v69
	ds_read_b128 v[172:175], v160 offset:4096
	ds_read_b128 v[168:171], v160 offset:4608
	s_waitcnt lgkmcnt(14)
	v_mfma_f32_32x32x16_bf16 v[0:15], v[136:139], v[120:123], v[0:15]
	v_exp_f32_e32 v70, v70
	v_exp_f32_e32 v71, v71
	ds_read_b128 v[164:167], v160 offset:6144
	ds_read_b128 v[160:163], v160 offset:6656
	s_waitcnt lgkmcnt(14)
	v_mfma_f32_32x32x16_bf16 v[16:31], v[132:135], v[124:127], v[16:31]
	v_exp_f32_e32 v72, v72
	v_exp_f32_e32 v73, v73
	s_mov_b64 s[34:35], 0xb72aa00
	v_lshl_add_u64 v[250:251], v[246:247], 0, s[34:35]
	s_lshl_b32 s3, s62, 13
	s_add_i32 s3, s3, s58
	s_mov_b32 m0, s3
	s_nop 0
	global_load_lds_dwordx4 v[250:251], off
	s_waitcnt lgkmcnt(12)
	v_mfma_f32_32x32x16_bf16 v[0:15], v[132:135], v[96:99], v[0:15]
	v_exp_f32_e32 v74, v74
	v_exp_f32_e32 v75, v75
	s_mov_b64 s[34:35], 0xb51ae00
	s_lshl_b32 s31, s61, 14
	v_lshl_add_u64 v[250:251], v[248:249], 0, s[34:35]
	s_add_i32 s3, s31, s59
	s_mov_b32 m0, s3
	s_nop 0
	global_load_lds_dwordx4 v[250:251], off
	s_waitcnt lgkmcnt(10)
	v_mfma_f32_32x32x16_bf16 v[16:31], v[128:131], v[100:103], v[16:31]
	v_exp_f32_e32 v76, v76
	v_exp_f32_e32 v77, v77
	s_mov_b64 s[34:35], 0xb51ae80
	v_lshl_add_u64 v[250:251], v[248:249], 0, s[34:35]
	s_addk_i32 s3, 0x2000
	s_mov_b32 m0, s3
	s_nop 0
	global_load_lds_dwordx4 v[250:251], off
	s_waitcnt lgkmcnt(8)
	v_mfma_f32_32x32x16_bf16 v[0:15], v[128:131], v[104:107], v[0:15]
	v_exp_f32_e32 v78, v78
	v_exp_f32_e32 v79, v79
	s_add_i32 s3, s61, 1
	s_waitcnt vmcnt(3) lgkmcnt(0)
	s_barrier
	s_cmp_lg_u32 s61, 2
	s_cselect_b32 s62, s3, 0
	s_add_i32 s33, s63, 2
	v_lshl_add_u64 v[192:193], v[192:193], 0, s[12:13]
	v_lshl_add_u64 v[194:195], v[194:195], 0, s[12:13]
	s_cmp_ge_u32 s60, s42
	v_lshl_add_u64 v[96:97], v[218:219], 0, s[12:13]
	s_mov_b32 s36, s30
	s_cbranch_scc0 .LBB0_442
	s_add_i32 s3, s60, 1
	s_cmp_ge_u32 s3, s41
	v_readlane_b32 s65, v252, 9
	s_cbranch_scc1 .LBB0_477

.LBB0_489:
	s_mov_b32 s14, s47
	v_mov_b64_e32 v[176:177], v[64:65]
	s_mov_b32 s21, s19
	v_lshl_add_u32 v168, s18, 13, v187
	ds_read_b64_tr_b16 v[164:165], v168 offset:24576
	ds_read_b64_tr_b16 v[166:167], v168 offset:25088
	v_mfma_f32_32x32x16_bf16 v[80:95], v[156:159], v[120:123], 0
	v_add_f32_e32 v64, v48, v49
	v_add_f32_e32 v64, v50, v64
	v_add_f32_e32 v64, v51, v64
	v_add_f32_e32 v64, v52, v64
	v_add_f32_e32 v64, v53, v64
	v_cvt_pk_bf16_f32 v108, v48, v49
	v_cvt_pk_bf16_f32 v109, v50, v51
	ds_read_b64_tr_b16 v[156:157], v168 offset:28672
	ds_read_b64_tr_b16 v[158:159], v168 offset:29184
	v_add_f32_e32 v48, v54, v64
	s_waitcnt lgkmcnt(10)
	v_mfma_f32_32x32x16_bf16 v[64:79], v[148:151], v[120:123], 0
	v_add_f32_e32 v48, v55, v48
	v_add_f32_e32 v48, v56, v48
	v_add_f32_e32 v96, v57, v48
	v_cvt_pk_bf16_f32 v110, v52, v53
	v_cvt_pk_bf16_f32 v111, v54, v55
	ds_read_b64_tr_b16 v[48:49], v168 offset:25600
	ds_read_b64_tr_b16 v[50:51], v168 offset:26112
	v_add_f32_e32 v52, v58, v96
	v_add_f32_e32 v52, v59, v52
	v_add_f32_e32 v52, v60, v52
	v_add_f32_e32 v96, v61, v52
	v_cvt_pk_bf16_f32 v104, v56, v57
	v_cvt_pk_bf16_f32 v105, v58, v59
	s_waitcnt lgkmcnt(11)
	v_mfma_f32_32x32x16_bf16 v[80:95], v[152:155], v[124:127], v[80:95]
	ds_read_b64_tr_b16 v[52:53], v168 offset:29696
	ds_read_b64_tr_b16 v[54:55], v168 offset:30208
	s_waitcnt lgkmcnt(12)
	v_mfma_f32_32x32x16_bf16 v[64:79], v[144:147], v[124:127], v[64:79]
	v_add_f32_e32 v56, v62, v96
	v_add_f32_e32 v56, v63, v56
	v_add_f32_e32 v56, v32, v56
	v_add_f32_e32 v96, v33, v56
	v_cvt_pk_bf16_f32 v106, v60, v61
	v_cvt_pk_bf16_f32 v107, v62, v63
	ds_read_b64_tr_b16 v[56:57], v168 offset:26624
	ds_read_b64_tr_b16 v[58:59], v168 offset:27136
	v_add_f32_e32 v60, v34, v96
	v_add_f32_e32 v60, v35, v60
	v_add_f32_e32 v60, v36, v60
	v_add_f32_e32 v60, v37, v60
	v_cvt_pk_bf16_f32 v100, v32, v33
	v_cvt_pk_bf16_f32 v101, v34, v35
	s_waitcnt lgkmcnt(13)
	v_mfma_f32_32x32x16_bf16 v[80:95], v[140:143], v[116:119], v[80:95]
	ds_read_b64_tr_b16 v[32:33], v168 offset:30720
	ds_read_b64_tr_b16 v[34:35], v168 offset:31232
	s_waitcnt lgkmcnt(14)
	v_mfma_f32_32x32x16_bf16 v[64:79], v[136:139], v[116:119], v[64:79]
	v_add_f32_e32 v60, v38, v60
	v_add_f32_e32 v60, v39, v60
	v_add_f32_e32 v60, v40, v60
	v_add_f32_e32 v60, v41, v60
	v_cvt_pk_bf16_f32 v102, v36, v37
	v_cvt_pk_bf16_f32 v103, v38, v39
	ds_read_b64_tr_b16 v[36:37], v168 offset:27648
	ds_read_b64_tr_b16 v[38:39], v168 offset:28160
	v_add_f32_e32 v60, v42, v60
	v_add_f32_e32 v60, v43, v60
	v_add_f32_e32 v60, v44, v60
	v_add_f32_e32 v60, v45, v60
	v_cvt_pk_bf16_f32 v96, v40, v41
	v_cvt_pk_bf16_f32 v97, v42, v43
	s_waitcnt lgkmcnt(14)
	v_mfma_f32_32x32x16_bf16 v[80:95], v[132:135], v[112:115], v[80:95]
	ds_read_b64_tr_b16 v[40:41], v168 offset:31744
	ds_read_b64_tr_b16 v[42:43], v168 offset:32256
	v_mfma_f32_32x32x16_bf16 v[64:79], v[128:131], v[112:115], v[64:79]
	v_add_f32_e32 v60, v46, v60
	v_add_f32_e32 v60, v47, v60
	v_add_f32_e32 v60, 0, v60
	v_cvt_pk_bf16_f32 v98, v44, v45
	v_cvt_pk_bf16_f32 v99, v46, v47
	v_lshl_add_u64 v[246:247], v[162:163], 0, s[0:1]
	s_lshl_b32 s3, s46, 13
	s_add_i32 s98, s3, s36
	v_lshl_add_u64 v[248:249], v[160:161], 0, s[0:1]
	s_lshl_b32 s33, s47, 13
	s_add_i32 s99, s33, s37
	v_add_f32_e32 v168, v188, v60
	s_waitcnt lgkmcnt(14)
	v_mfma_f32_32x32x16_bf16 v[0:15], v[108:111], v[164:167], v[0:15]
	v_exp_f32_e32 v80, v80
	v_exp_f32_e32 v81, v81
	v_exp_f32_e32 v82, v82
	v_exp_f32_e32 v83, v83
	s_waitcnt lgkmcnt(12)
	v_mfma_f32_32x32x16_bf16 v[16:31], v[108:111], v[156:159], v[16:31]
	v_exp_f32_e32 v84, v84
	v_exp_f32_e32 v85, v85
	v_exp_f32_e32 v86, v86
	v_exp_f32_e32 v87, v87
	v_add_u32_e32 v60, s33, v185
	ds_read_b128 v[44:47], v60
	ds_read_b128 v[136:139], v60 offset:512
	s_waitcnt lgkmcnt(12)
	v_mfma_f32_32x32x16_bf16 v[0:15], v[104:107], v[48:51], v[0:15]
	v_exp_f32_e32 v88, v88
	v_exp_f32_e32 v89, v89
	v_exp_f32_e32 v90, v90
	v_exp_f32_e32 v91, v91
	ds_read_b128 v[140:143], v60 offset:2048
	ds_read_b128 v[144:147], v60 offset:2560
	s_waitcnt lgkmcnt(12)
	v_mfma_f32_32x32x16_bf16 v[16:31], v[104:107], v[52:55], v[16:31]
	v_exp_f32_e32 v92, v92
	v_exp_f32_e32 v93, v93
	v_exp_f32_e32 v94, v94
	v_exp_f32_e32 v95, v95
	ds_read_b128 v[148:151], v60 offset:4096
	ds_read_b128 v[152:155], v60 offset:4608
	s_waitcnt lgkmcnt(12)
	v_mfma_f32_32x32x16_bf16 v[0:15], v[100:103], v[56:59], v[0:15]
	v_exp_f32_e32 v64, v64
	v_exp_f32_e32 v65, v65
	v_exp_f32_e32 v66, v66
	v_exp_f32_e32 v67, v67
	ds_read_b128 v[156:159], v60 offset:6144
	ds_read_b128 v[128:131], v60 offset:6656
	s_waitcnt lgkmcnt(12)
	v_mfma_f32_32x32x16_bf16 v[16:31], v[100:103], v[32:35], v[16:31]
	v_exp_f32_e32 v68, v68
	v_exp_f32_e32 v69, v69
	v_exp_f32_e32 v70, v70
	v_exp_f32_e32 v71, v71
	s_mov_b64 s[16:17], 0xb622100
	v_lshl_add_u64 v[250:251], v[246:247], 0, s[16:17]
	s_mov_b32 m0, s98
	s_nop 0
	global_load_lds_dwordx4 v[250:251], off
	s_waitcnt lgkmcnt(10)
	v_mfma_f32_32x32x16_bf16 v[0:15], v[96:99], v[36:39], v[0:15]
	v_exp_f32_e32 v72, v72
	v_exp_f32_e32 v73, v73
	v_exp_f32_e32 v74, v74
	v_exp_f32_e32 v75, v75
	s_mov_b64 s[16:17], 0xb412200
	v_lshl_add_u64 v[250:251], v[248:249], 0, s[16:17]
	s_mov_b32 m0, s99
	s_nop 0
	global_load_lds_dwordx4 v[250:251], off
	s_waitcnt lgkmcnt(8)
	v_mfma_f32_32x32x16_bf16 v[16:31], v[96:99], v[40:43], v[16:31]
	v_exp_f32_e32 v76, v76
	v_exp_f32_e32 v77, v77
	v_exp_f32_e32 v78, v78
	v_exp_f32_e32 v79, v79
	s_waitcnt vmcnt(2) lgkmcnt(0)
	s_barrier
	s_add_i32 s15, s47, 1
	s_cmp_lg_u32 s47, 2
	s_cselect_b32 s46, s15, 0
	v_add_u32_e32 v169, s3, v187
	ds_read_b64_tr_b16 v[164:165], v169 offset:24576
	ds_read_b64_tr_b16 v[166:167], v169 offset:25088
	s_waitcnt lgkmcnt(9)
	v_mfma_f32_32x32x16_bf16 v[48:63], v[44:47], v[120:123], 0
	v_add_f32_e32 v32, v80, v81
	v_add_f32_e32 v32, v82, v32
	v_add_f32_e32 v32, v83, v32
	v_add_f32_e32 v32, v84, v32
	v_add_f32_e32 v32, v85, v32
	v_cvt_pk_bf16_f32 v108, v80, v81
	v_cvt_pk_bf16_f32 v109, v82, v83
	ds_read_b64_tr_b16 v[80:81], v169 offset:28672
	ds_read_b64_tr_b16 v[82:83], v169 offset:29184
	v_add_f32_e32 v32, v86, v32
	v_add_f32_e32 v32, v87, v32
	v_add_f32_e32 v32, v88, v32
	v_add_f32_e32 v96, v89, v32
	s_waitcnt lgkmcnt(10)
	v_mfma_f32_32x32x16_bf16 v[32:47], v[136:139], v[120:123], 0
	v_cvt_pk_bf16_f32 v110, v84, v85
	v_cvt_pk_bf16_f32 v111, v86, v87
	ds_read_b64_tr_b16 v[84:85], v169 offset:25600
	ds_read_b64_tr_b16 v[86:87], v169 offset:26112
	s_waitcnt lgkmcnt(11)
	v_mfma_f32_32x32x16_bf16 v[48:63], v[140:143], v[124:127], v[48:63]
	v_add_f32_e32 v96, v90, v96
	v_add_f32_e32 v96, v91, v96
	v_add_f32_e32 v96, v92, v96
	v_add_f32_e32 v96, v93, v96
	v_cvt_pk_bf16_f32 v104, v88, v89
	v_cvt_pk_bf16_f32 v105, v90, v91
	ds_read_b64_tr_b16 v[88:89], v169 offset:29696
	ds_read_b64_tr_b16 v[90:91], v169 offset:30208
	s_waitcnt lgkmcnt(12)
	v_mfma_f32_32x32x16_bf16 v[32:47], v[144:147], v[124:127], v[32:47]
	v_add_f32_e32 v96, v94, v96
	v_add_f32_e32 v96, v95, v96
	v_add_f32_e32 v96, v64, v96
	v_add_f32_e32 v96, v65, v96
	v_cvt_pk_bf16_f32 v106, v92, v93
	v_cvt_pk_bf16_f32 v107, v94, v95
	ds_read_b64_tr_b16 v[92:93], v169 offset:26624
	ds_read_b64_tr_b16 v[94:95], v169 offset:27136
	s_waitcnt lgkmcnt(13)
	v_mfma_f32_32x32x16_bf16 v[48:63], v[148:151], v[116:119], v[48:63]
	v_add_f32_e32 v96, v66, v96
	v_add_f32_e32 v96, v67, v96
	v_add_f32_e32 v96, v68, v96
	v_add_f32_e32 v96, v69, v96
	v_cvt_pk_bf16_f32 v100, v64, v65
	v_cvt_pk_bf16_f32 v101, v66, v67
	ds_read_b64_tr_b16 v[64:65], v169 offset:30720
	ds_read_b64_tr_b16 v[66:67], v169 offset:31232
	s_waitcnt lgkmcnt(14)
	v_mfma_f32_32x32x16_bf16 v[32:47], v[152:155], v[116:119], v[32:47]
	v_add_f32_e32 v96, v70, v96
	v_add_f32_e32 v96, v71, v96
	v_add_f32_e32 v96, v72, v96
	v_add_f32_e32 v96, v73, v96
	v_cvt_pk_bf16_f32 v102, v68, v69
	v_cvt_pk_bf16_f32 v103, v70, v71
	ds_read_b64_tr_b16 v[68:69], v169 offset:27648
	ds_read_b64_tr_b16 v[70:71], v169 offset:28160
	s_waitcnt lgkmcnt(14)
	v_mfma_f32_32x32x16_bf16 v[48:63], v[156:159], v[112:115], v[48:63]
	v_add_f32_e32 v96, v74, v96
	v_add_f32_e32 v96, v75, v96
	v_add_f32_e32 v96, v76, v96
	v_add_f32_e32 v136, v77, v96
	v_cvt_pk_bf16_f32 v96, v72, v73
	v_cvt_pk_bf16_f32 v97, v74, v75
	ds_read_b64_tr_b16 v[72:73], v169 offset:31744
	ds_read_b64_tr_b16 v[74:75], v169 offset:32256
	v_mfma_f32_32x32x16_bf16 v[32:47], v[128:131], v[112:115], v[32:47]
	v_add_f32_e32 v98, v78, v136
	v_add_f32_e32 v98, v79, v98
	v_add_f32_e32 v128, 0, v98
	v_cvt_pk_bf16_f32 v98, v76, v77
	v_cvt_pk_bf16_f32 v99, v78, v79
	s_add_i32 s98, s33, s36
	s_lshl_b32 s15, s46, 13
	s_add_i32 s99, s15, s37
	v_add_f32_e32 v188, v168, v128
	s_add_i32 s20, s20, 2
	s_waitcnt lgkmcnt(14)
	v_mfma_f32_32x32x16_bf16 v[0:15], v[108:111], v[164:167], v[0:15]
	v_exp_f32_e32 v48, v48
	v_exp_f32_e32 v49, v49
	v_exp_f32_e32 v50, v50
	v_exp_f32_e32 v51, v51
	s_waitcnt lgkmcnt(12)
	v_mfma_f32_32x32x16_bf16 v[16:31], v[108:111], v[80:83], v[16:31]
	v_exp_f32_e32 v52, v52
	v_exp_f32_e32 v53, v53
	v_exp_f32_e32 v54, v54
	v_exp_f32_e32 v55, v55
	v_add_u32_e32 v76, s15, v185
	ds_read_b128 v[156:159], v76
	ds_read_b128 v[148:151], v76 offset:512
	s_waitcnt lgkmcnt(12)
	v_mfma_f32_32x32x16_bf16 v[0:15], v[104:107], v[84:87], v[0:15]
	v_exp_f32_e32 v56, v56
	v_exp_f32_e32 v57, v57
	v_exp_f32_e32 v58, v58
	v_exp_f32_e32 v59, v59
	ds_read_b128 v[152:155], v76 offset:2048
	ds_read_b128 v[144:147], v76 offset:2560
	s_waitcnt lgkmcnt(12)
	v_mfma_f32_32x32x16_bf16 v[16:31], v[104:107], v[88:91], v[16:31]
	v_exp_f32_e32 v60, v60
	v_exp_f32_e32 v61, v61
	v_exp_f32_e32 v62, v62
	v_exp_f32_e32 v63, v63
	ds_read_b128 v[140:143], v76 offset:4096
	ds_read_b128 v[136:139], v76 offset:4608
	s_waitcnt lgkmcnt(12)
	v_mfma_f32_32x32x16_bf16 v[0:15], v[100:103], v[92:95], v[0:15]
	v_exp_f32_e32 v32, v32
	v_exp_f32_e32 v33, v33
	v_exp_f32_e32 v34, v34
	v_exp_f32_e32 v35, v35
	ds_read_b128 v[132:135], v76 offset:6144
	ds_read_b128 v[128:131], v76 offset:6656
	s_waitcnt lgkmcnt(12)
	v_mfma_f32_32x32x16_bf16 v[16:31], v[100:103], v[64:67], v[16:31]
	v_exp_f32_e32 v36, v36
	v_exp_f32_e32 v37, v37
	v_exp_f32_e32 v38, v38
	v_exp_f32_e32 v39, v39
	s_mov_b64 s[16:17], 0xb72a100
	v_lshl_add_u64 v[250:251], v[246:247], 0, s[16:17]
	s_mov_b32 m0, s98
	s_nop 0
	global_load_lds_dwordx4 v[250:251], off
	s_waitcnt lgkmcnt(10)
	v_mfma_f32_32x32x16_bf16 v[0:15], v[96:99], v[68:71], v[0:15]
	v_exp_f32_e32 v40, v40
	v_exp_f32_e32 v41, v41
	v_exp_f32_e32 v42, v42
	v_exp_f32_e32 v43, v43
	s_mov_b64 s[16:17], 0xb51a200
	v_lshl_add_u64 v[250:251], v[248:249], 0, s[16:17]
	s_mov_b32 m0, s99
	s_nop 0
	global_load_lds_dwordx4 v[250:251], off
	s_waitcnt lgkmcnt(8)
	v_mfma_f32_32x32x16_bf16 v[16:31], v[96:99], v[72:75], v[16:31]
	v_exp_f32_e32 v44, v44
	v_exp_f32_e32 v45, v45
	v_exp_f32_e32 v46, v46
	v_exp_f32_e32 v47, v47
	s_add_i32 s3, s46, 1
	s_waitcnt vmcnt(2) lgkmcnt(0)
	s_barrier
	s_cmp_lg_u32 s46, 2
	s_cselect_b32 s47, s3, 0
	s_add_i32 s19, s19, 2
	v_lshl_add_u64 v[160:161], v[160:161], 0, s[12:13]
	v_lshl_add_u64 v[162:163], v[162:163], 0, s[12:13]
	s_cmp_ge_u32 s20, s42
	v_lshl_add_u64 v[64:65], v[176:177], 0, s[12:13]
	s_mov_b32 s18, s14
	s_cbranch_scc0 .LBB0_489
	s_add_i32 s0, s20, 1
	s_cmp_ge_u32 s0, s41
	s_cbranch_scc1 .LBB0_524
